# v010 plus out-proj epilogue (phases 3,8): all 64 residual loads issued up front with SGPR-base addressing, then add and store under vmcnt(63)
# speedup vs baseline: 1.0023x; 1.0023x over previous
;     ...
;     for (int mf = 0; mf < 4; ++mf) {
;       __builtin_amdgcn_sched_barrier(0);
;       float rvv[4][4];
;       if (EPI == 1) {
; #pragma unroll
;         for (int r = 0; r < 4; ++r) {
;           const int row = m0 + wm * 64 + mf * 16 + 4 * g + r;
; #pragma unroll
;           for (int nf = 0; nf < 4; ++nf) {
;             const int col = n0 + wn * 64 + nf * 16 + l15;
;             rvv[r][nf] = resid ? resid[(size_t)row * 1024 + col] : xrow(p, row)[col];
;           }
;         }
;       }
;     ...
;         } else if (EPI == 1) {
; #pragma unroll
;           for (int nf = 0; nf < 4; ++nf) {
;             const int col = n0 + wn * 64 + nf * 16 + l15;
;             const float a = (NH > 0) ? accT[mf][nf][r] : acc[mf][nf][r];
;             outf[(size_t)row * 1024 + col] = rvv[r][nf] + a;
;           }
.LBB0_706:
	v_add_u32_e32 v214, s31, v201
	v_or_b32_e32 v215, s33, v200
	v_lshlrev_b32_e32 v214, 12, v214
	v_lshl_add_u32 v214, v215, 2, v214
	v_add_u32_e32 v215, 0x1000, v214
	v_add_u32_e32 v216, 0x2000, v214
	v_add_u32_e32 v217, 0x3000, v214
	v_add_u32_e32 v218, 0x10000, v214
	v_add_u32_e32 v219, 0x11000, v214
	v_add_u32_e32 v220, 0x12000, v214
	v_add_u32_e32 v221, 0x13000, v214
	v_add_u32_e32 v222, 0x20000, v214
	v_add_u32_e32 v223, 0x21000, v214
	v_add_u32_e32 v224, 0x22000, v214
	v_add_u32_e32 v225, 0x23000, v214
	v_add_u32_e32 v226, 0x30000, v214
	v_add_u32_e32 v227, 0x31000, v214
	v_add_u32_e32 v228, 0x32000, v214
	v_add_u32_e32 v229, 0x33000, v214
	global_load_dword v116, v214, s[8:9]
	global_load_dword v117, v214, s[8:9] offset:64
	global_load_dword v118, v214, s[8:9] offset:128
	global_load_dword v119, v214, s[8:9] offset:192
	global_load_dword v120, v215, s[8:9]
	global_load_dword v121, v215, s[8:9] offset:64
	global_load_dword v122, v215, s[8:9] offset:128
	global_load_dword v123, v215, s[8:9] offset:192
	global_load_dword v124, v216, s[8:9]
	global_load_dword v125, v216, s[8:9] offset:64
	global_load_dword v126, v216, s[8:9] offset:128
	global_load_dword v127, v216, s[8:9] offset:192
	global_load_dword v128, v217, s[8:9]
	global_load_dword v129, v217, s[8:9] offset:64
	global_load_dword v130, v217, s[8:9] offset:128
	global_load_dword v131, v217, s[8:9] offset:192
	global_load_dword v132, v218, s[8:9]
	global_load_dword v133, v218, s[8:9] offset:64
	global_load_dword v134, v218, s[8:9] offset:128
	global_load_dword v135, v218, s[8:9] offset:192
	global_load_dword v136, v219, s[8:9]
	global_load_dword v137, v219, s[8:9] offset:64
	global_load_dword v138, v219, s[8:9] offset:128
	global_load_dword v139, v219, s[8:9] offset:192
	global_load_dword v140, v220, s[8:9]
	global_load_dword v141, v220, s[8:9] offset:64
	global_load_dword v142, v220, s[8:9] offset:128
	global_load_dword v143, v220, s[8:9] offset:192
	global_load_dword v144, v221, s[8:9]
	global_load_dword v145, v221, s[8:9] offset:64
	global_load_dword v146, v221, s[8:9] offset:128
	global_load_dword v147, v221, s[8:9] offset:192
	global_load_dword v148, v222, s[8:9]
	global_load_dword v149, v222, s[8:9] offset:64
	global_load_dword v150, v222, s[8:9] offset:128
	global_load_dword v151, v222, s[8:9] offset:192
	global_load_dword v152, v223, s[8:9]
	global_load_dword v153, v223, s[8:9] offset:64
	global_load_dword v154, v223, s[8:9] offset:128
	global_load_dword v155, v223, s[8:9] offset:192
	global_load_dword v156, v224, s[8:9]
	global_load_dword v157, v224, s[8:9] offset:64
	global_load_dword v158, v224, s[8:9] offset:128
	global_load_dword v159, v224, s[8:9] offset:192
	global_load_dword v160, v225, s[8:9]
	global_load_dword v161, v225, s[8:9] offset:64
	global_load_dword v162, v225, s[8:9] offset:128
	global_load_dword v163, v225, s[8:9] offset:192
	global_load_dword v164, v226, s[8:9]
	global_load_dword v165, v226, s[8:9] offset:64
	global_load_dword v166, v226, s[8:9] offset:128
	global_load_dword v167, v226, s[8:9] offset:192
	global_load_dword v168, v227, s[8:9]
	global_load_dword v169, v227, s[8:9] offset:64
	global_load_dword v170, v227, s[8:9] offset:128
	global_load_dword v171, v227, s[8:9] offset:192
	global_load_dword v172, v228, s[8:9]
	global_load_dword v173, v228, s[8:9] offset:64
	global_load_dword v174, v228, s[8:9] offset:128
	global_load_dword v175, v228, s[8:9] offset:192
	global_load_dword v176, v229, s[8:9]
	global_load_dword v177, v229, s[8:9] offset:64
	global_load_dword v178, v229, s[8:9] offset:128
	global_load_dword v179, v229, s[8:9] offset:192
	s_waitcnt vmcnt(63)
	v_add_f32_e32 v116, v64, v116
	global_store_dword v214, v116, s[6:7]
	s_waitcnt vmcnt(63)
	v_add_f32_e32 v117, v60, v117
	global_store_dword v214, v117, s[6:7] offset:64
	s_waitcnt vmcnt(63)
	v_add_f32_e32 v118, v56, v118
	global_store_dword v214, v118, s[6:7] offset:128
	s_waitcnt vmcnt(63)
	v_add_f32_e32 v119, v52, v119
	global_store_dword v214, v119, s[6:7] offset:192
	s_waitcnt vmcnt(63)
	v_add_f32_e32 v120, v65, v120
	global_store_dword v215, v120, s[6:7]
	s_waitcnt vmcnt(63)
	v_add_f32_e32 v121, v61, v121
	global_store_dword v215, v121, s[6:7] offset:64
	s_waitcnt vmcnt(63)
	v_add_f32_e32 v122, v57, v122
	global_store_dword v215, v122, s[6:7] offset:128
	s_waitcnt vmcnt(63)
	v_add_f32_e32 v123, v53, v123
	global_store_dword v215, v123, s[6:7] offset:192
	s_waitcnt vmcnt(63)
	v_add_f32_e32 v124, v66, v124
	global_store_dword v216, v124, s[6:7]
	s_waitcnt vmcnt(63)
	v_add_f32_e32 v125, v62, v125
	global_store_dword v216, v125, s[6:7] offset:64
	s_waitcnt vmcnt(63)
	v_add_f32_e32 v126, v58, v126
	global_store_dword v216, v126, s[6:7] offset:128
	s_waitcnt vmcnt(63)
	v_add_f32_e32 v127, v54, v127
	global_store_dword v216, v127, s[6:7] offset:192
	s_waitcnt vmcnt(63)
	v_add_f32_e32 v128, v67, v128
	global_store_dword v217, v128, s[6:7]
	s_waitcnt vmcnt(63)
	v_add_f32_e32 v129, v63, v129
	global_store_dword v217, v129, s[6:7] offset:64
	s_waitcnt vmcnt(63)
;     ...
;         } else if (EPI == 1) {
; #pragma unroll
;           for (int nf = 0; nf < 4; ++nf) {
;             const int col = n0 + wn * 64 + nf * 16 + l15;
;             const float a = (NH > 0) ? accT[mf][nf][r] : acc[mf][nf][r];
;             outf[(size_t)row * 1024 + col] = rvv[r][nf] + a;
;           }
	v_add_f32_e32 v130, v59, v130
	global_store_dword v217, v130, s[6:7] offset:128
	s_waitcnt vmcnt(63)
	v_add_f32_e32 v131, v55, v131
	global_store_dword v217, v131, s[6:7] offset:192
	s_waitcnt vmcnt(63)
	v_add_f32_e32 v132, v48, v132
	global_store_dword v218, v132, s[6:7]
	s_waitcnt vmcnt(63)
	v_add_f32_e32 v133, v44, v133
	global_store_dword v218, v133, s[6:7] offset:64
	s_waitcnt vmcnt(63)
	v_add_f32_e32 v134, v40, v134
	global_store_dword v218, v134, s[6:7] offset:128
	s_waitcnt vmcnt(63)
	v_add_f32_e32 v135, v36, v135
	global_store_dword v218, v135, s[6:7] offset:192
	s_waitcnt vmcnt(63)
	v_add_f32_e32 v136, v49, v136
	global_store_dword v219, v136, s[6:7]
	s_waitcnt vmcnt(63)
	v_add_f32_e32 v137, v45, v137
	global_store_dword v219, v137, s[6:7] offset:64
	s_waitcnt vmcnt(63)
	v_add_f32_e32 v138, v41, v138
	global_store_dword v219, v138, s[6:7] offset:128
	s_waitcnt vmcnt(63)
	v_add_f32_e32 v139, v37, v139
	global_store_dword v219, v139, s[6:7] offset:192
	s_waitcnt vmcnt(63)
	v_add_f32_e32 v140, v50, v140
	global_store_dword v220, v140, s[6:7]
	s_waitcnt vmcnt(63)
	v_add_f32_e32 v141, v46, v141
	global_store_dword v220, v141, s[6:7] offset:64
	s_waitcnt vmcnt(63)
	v_add_f32_e32 v142, v42, v142
	global_store_dword v220, v142, s[6:7] offset:128
	s_waitcnt vmcnt(63)
	v_add_f32_e32 v143, v38, v143
	global_store_dword v220, v143, s[6:7] offset:192
	s_waitcnt vmcnt(63)
	v_add_f32_e32 v144, v51, v144
	global_store_dword v221, v144, s[6:7]
	s_waitcnt vmcnt(63)
	v_add_f32_e32 v145, v47, v145
	global_store_dword v221, v145, s[6:7] offset:64
	s_waitcnt vmcnt(63)
	v_add_f32_e32 v146, v43, v146
	global_store_dword v221, v146, s[6:7] offset:128
	s_waitcnt vmcnt(63)
	v_add_f32_e32 v147, v39, v147
	global_store_dword v221, v147, s[6:7] offset:192
	s_waitcnt vmcnt(63)
	v_add_f32_e32 v148, v32, v148
	global_store_dword v222, v148, s[6:7]
	s_waitcnt vmcnt(63)
	v_add_f32_e32 v149, v28, v149
	global_store_dword v222, v149, s[6:7] offset:64
	s_waitcnt vmcnt(63)
	v_add_f32_e32 v150, v24, v150
	global_store_dword v222, v150, s[6:7] offset:128
	s_waitcnt vmcnt(63)
	v_add_f32_e32 v151, v20, v151
	global_store_dword v222, v151, s[6:7] offset:192
	s_waitcnt vmcnt(63)
	v_add_f32_e32 v152, v33, v152
	global_store_dword v223, v152, s[6:7]
	s_waitcnt vmcnt(63)
	v_add_f32_e32 v153, v29, v153
	global_store_dword v223, v153, s[6:7] offset:64
	s_waitcnt vmcnt(63)
	v_add_f32_e32 v154, v25, v154
	global_store_dword v223, v154, s[6:7] offset:128
	s_waitcnt vmcnt(63)
	v_add_f32_e32 v155, v21, v155
	global_store_dword v223, v155, s[6:7] offset:192
	s_waitcnt vmcnt(63)
	v_add_f32_e32 v156, v34, v156
	global_store_dword v224, v156, s[6:7]
	s_waitcnt vmcnt(63)
	v_add_f32_e32 v157, v30, v157
	global_store_dword v224, v157, s[6:7] offset:64
	s_waitcnt vmcnt(63)
	v_add_f32_e32 v158, v26, v158
	global_store_dword v224, v158, s[6:7] offset:128
	s_waitcnt vmcnt(63)
	v_add_f32_e32 v159, v22, v159
	global_store_dword v224, v159, s[6:7] offset:192
	s_waitcnt vmcnt(63)
	v_add_f32_e32 v160, v35, v160
	global_store_dword v225, v160, s[6:7]
	s_waitcnt vmcnt(63)
	v_add_f32_e32 v161, v31, v161
	global_store_dword v225, v161, s[6:7] offset:64
	s_waitcnt vmcnt(63)
	v_add_f32_e32 v162, v27, v162
	global_store_dword v225, v162, s[6:7] offset:128
	s_waitcnt vmcnt(63)
	v_add_f32_e32 v163, v23, v163
	global_store_dword v225, v163, s[6:7] offset:192
	s_waitcnt vmcnt(63)
	v_add_f32_e32 v164, v16, v164
	global_store_dword v226, v164, s[6:7]
	s_waitcnt vmcnt(63)
	v_add_f32_e32 v165, v12, v165
	global_store_dword v226, v165, s[6:7] offset:64
	s_waitcnt vmcnt(63)
	v_add_f32_e32 v166, v8, v166
	global_store_dword v226, v166, s[6:7] offset:128
	s_waitcnt vmcnt(63)
	v_add_f32_e32 v167, v4, v167
	global_store_dword v226, v167, s[6:7] offset:192
	s_waitcnt vmcnt(63)
	v_add_f32_e32 v168, v17, v168
	global_store_dword v227, v168, s[6:7]
	s_waitcnt vmcnt(63)
	v_add_f32_e32 v169, v13, v169
	global_store_dword v227, v169, s[6:7] offset:64
	s_waitcnt vmcnt(63)
	v_add_f32_e32 v170, v9, v170
	global_store_dword v227, v170, s[6:7] offset:128
	s_waitcnt vmcnt(63)
	v_add_f32_e32 v171, v5, v171
	global_store_dword v227, v171, s[6:7] offset:192
	s_waitcnt vmcnt(63)
	v_add_f32_e32 v172, v18, v172
	global_store_dword v228, v172, s[6:7]
	s_waitcnt vmcnt(63)
	v_add_f32_e32 v173, v14, v173
	global_store_dword v228, v173, s[6:7] offset:64
	s_waitcnt vmcnt(63)
	v_add_f32_e32 v174, v10, v174
	global_store_dword v228, v174, s[6:7] offset:128
	s_waitcnt vmcnt(63)
	v_add_f32_e32 v175, v6, v175
	global_store_dword v228, v175, s[6:7] offset:192
	s_waitcnt vmcnt(63)
	v_add_f32_e32 v176, v19, v176
	global_store_dword v229, v176, s[6:7]
	s_waitcnt vmcnt(63)
	v_add_f32_e32 v177, v15, v177
	global_store_dword v229, v177, s[6:7] offset:64
	s_waitcnt vmcnt(63)
	v_add_f32_e32 v178, v11, v178
	global_store_dword v229, v178, s[6:7] offset:128
	s_waitcnt vmcnt(63)
	v_add_f32_e32 v179, v7, v179
	global_store_dword v229, v179, s[6:7] offset:192
	s_add_i32 s30, s30, s96
	s_cmp_ge_i32 s30, s25
	s_cbranch_scc1 .LBB0_723

;     ...
;     for (int mf = 0; mf < 4; ++mf) {
;       __builtin_amdgcn_sched_barrier(0);
;       float rvv[4][4];
;       if (EPI == 1) {
; #pragma unroll
;         for (int r = 0; r < 4; ++r) {
;           const int row = m0 + wm * 64 + mf * 16 + 4 * g + r;
; #pragma unroll
;           for (int nf = 0; nf < 4; ++nf) {
;             const int col = n0 + wn * 64 + nf * 16 + l15;
;             rvv[r][nf] = resid ? resid[(size_t)row * 1024 + col] : xrow(p, row)[col];
;           }
;         }
;       }
;     ...
;         } else if (EPI == 1) {
; #pragma unroll
;           for (int nf = 0; nf < 4; ++nf) {
;             const int col = n0 + wn * 64 + nf * 16 + l15;
;             const float a = (NH > 0) ? accT[mf][nf][r] : acc[mf][nf][r];
;             outf[(size_t)row * 1024 + col] = rvv[r][nf] + a;
;           }
.LBB0_2011:
	v_add_u32_e32 v214, s28, v201
	v_or_b32_e32 v215, s29, v200
	v_lshlrev_b32_e32 v214, 12, v214
	v_lshl_add_u32 v214, v215, 2, v214
	v_add_u32_e32 v215, 0x1000, v214
	v_add_u32_e32 v216, 0x2000, v214
	v_add_u32_e32 v217, 0x3000, v214
	v_add_u32_e32 v218, 0x10000, v214
	v_add_u32_e32 v219, 0x11000, v214
	v_add_u32_e32 v220, 0x12000, v214
	v_add_u32_e32 v221, 0x13000, v214
	v_add_u32_e32 v222, 0x20000, v214
	v_add_u32_e32 v223, 0x21000, v214
	v_add_u32_e32 v224, 0x22000, v214
	v_add_u32_e32 v225, 0x23000, v214
	v_add_u32_e32 v226, 0x30000, v214
	v_add_u32_e32 v227, 0x31000, v214
	v_add_u32_e32 v228, 0x32000, v214
	v_add_u32_e32 v229, 0x33000, v214
	global_load_dword v116, v214, s[6:7]
	global_load_dword v117, v214, s[6:7] offset:64
	global_load_dword v118, v214, s[6:7] offset:128
	global_load_dword v119, v214, s[6:7] offset:192
	global_load_dword v120, v215, s[6:7]
	global_load_dword v121, v215, s[6:7] offset:64
	global_load_dword v122, v215, s[6:7] offset:128
	global_load_dword v123, v215, s[6:7] offset:192
	global_load_dword v124, v216, s[6:7]
	global_load_dword v125, v216, s[6:7] offset:64
	global_load_dword v126, v216, s[6:7] offset:128
	global_load_dword v127, v216, s[6:7] offset:192
	global_load_dword v128, v217, s[6:7]
	global_load_dword v129, v217, s[6:7] offset:64
	global_load_dword v130, v217, s[6:7] offset:128
	global_load_dword v131, v217, s[6:7] offset:192
	global_load_dword v132, v218, s[6:7]
	global_load_dword v133, v218, s[6:7] offset:64
	global_load_dword v134, v218, s[6:7] offset:128
	global_load_dword v135, v218, s[6:7] offset:192
	global_load_dword v136, v219, s[6:7]
	global_load_dword v137, v219, s[6:7] offset:64
	global_load_dword v138, v219, s[6:7] offset:128
	global_load_dword v139, v219, s[6:7] offset:192
	global_load_dword v140, v220, s[6:7]
	global_load_dword v141, v220, s[6:7] offset:64
	global_load_dword v142, v220, s[6:7] offset:128
	global_load_dword v143, v220, s[6:7] offset:192
	global_load_dword v144, v221, s[6:7]
	global_load_dword v145, v221, s[6:7] offset:64
	global_load_dword v146, v221, s[6:7] offset:128
	global_load_dword v147, v221, s[6:7] offset:192
	global_load_dword v148, v222, s[6:7]
	global_load_dword v149, v222, s[6:7] offset:64
	global_load_dword v150, v222, s[6:7] offset:128
	global_load_dword v151, v222, s[6:7] offset:192
	global_load_dword v152, v223, s[6:7]
	global_load_dword v153, v223, s[6:7] offset:64
	global_load_dword v154, v223, s[6:7] offset:128
	global_load_dword v155, v223, s[6:7] offset:192
	global_load_dword v156, v224, s[6:7]
	global_load_dword v157, v224, s[6:7] offset:64
	global_load_dword v158, v224, s[6:7] offset:128
	global_load_dword v159, v224, s[6:7] offset:192
	global_load_dword v160, v225, s[6:7]
	global_load_dword v161, v225, s[6:7] offset:64
	global_load_dword v162, v225, s[6:7] offset:128
	global_load_dword v163, v225, s[6:7] offset:192
	global_load_dword v164, v226, s[6:7]
	global_load_dword v165, v226, s[6:7] offset:64
	global_load_dword v166, v226, s[6:7] offset:128
	global_load_dword v167, v226, s[6:7] offset:192
	global_load_dword v168, v227, s[6:7]
	global_load_dword v169, v227, s[6:7] offset:64
	global_load_dword v170, v227, s[6:7] offset:128
	global_load_dword v171, v227, s[6:7] offset:192
	global_load_dword v172, v228, s[6:7]
	global_load_dword v173, v228, s[6:7] offset:64
	global_load_dword v174, v228, s[6:7] offset:128
	global_load_dword v175, v228, s[6:7] offset:192
	global_load_dword v176, v229, s[6:7]
	global_load_dword v177, v229, s[6:7] offset:64
	global_load_dword v178, v229, s[6:7] offset:128
	global_load_dword v179, v229, s[6:7] offset:192
	s_waitcnt vmcnt(63)
	v_add_f32_e32 v116, v64, v116
	global_store_dword v214, v116, s[8:9]
	s_waitcnt vmcnt(63)
	v_add_f32_e32 v117, v60, v117
	global_store_dword v214, v117, s[8:9] offset:64
	s_waitcnt vmcnt(63)
	v_add_f32_e32 v118, v56, v118
	global_store_dword v214, v118, s[8:9] offset:128
	s_waitcnt vmcnt(63)
	v_add_f32_e32 v119, v52, v119
	global_store_dword v214, v119, s[8:9] offset:192
	s_waitcnt vmcnt(63)
	v_add_f32_e32 v120, v65, v120
	global_store_dword v215, v120, s[8:9]
	s_waitcnt vmcnt(63)
	v_add_f32_e32 v121, v61, v121
	global_store_dword v215, v121, s[8:9] offset:64
	s_waitcnt vmcnt(63)
	v_add_f32_e32 v122, v57, v122
	global_store_dword v215, v122, s[8:9] offset:128
	s_waitcnt vmcnt(63)
	v_add_f32_e32 v123, v53, v123
	global_store_dword v215, v123, s[8:9] offset:192
	s_waitcnt vmcnt(63)
	v_add_f32_e32 v124, v66, v124
	global_store_dword v216, v124, s[8:9]
	s_waitcnt vmcnt(63)
	v_add_f32_e32 v125, v62, v125
	global_store_dword v216, v125, s[8:9] offset:64
	s_waitcnt vmcnt(63)
	v_add_f32_e32 v126, v58, v126
	global_store_dword v216, v126, s[8:9] offset:128
	s_waitcnt vmcnt(63)
	v_add_f32_e32 v127, v54, v127
	global_store_dword v216, v127, s[8:9] offset:192
	s_waitcnt vmcnt(63)
	v_add_f32_e32 v128, v67, v128
	global_store_dword v217, v128, s[8:9]
	s_waitcnt vmcnt(63)
	v_add_f32_e32 v129, v63, v129
	global_store_dword v217, v129, s[8:9] offset:64
	s_waitcnt vmcnt(63)
;     ...
;         } else if (EPI == 1) {
; #pragma unroll
;           for (int nf = 0; nf < 4; ++nf) {
;             const int col = n0 + wn * 64 + nf * 16 + l15;
;             const float a = (NH > 0) ? accT[mf][nf][r] : acc[mf][nf][r];
;             outf[(size_t)row * 1024 + col] = rvv[r][nf] + a;
;           }
	v_add_f32_e32 v130, v59, v130
	global_store_dword v217, v130, s[8:9] offset:128
	s_waitcnt vmcnt(63)
	v_add_f32_e32 v131, v55, v131
	global_store_dword v217, v131, s[8:9] offset:192
	s_waitcnt vmcnt(63)
	v_add_f32_e32 v132, v48, v132
	global_store_dword v218, v132, s[8:9]
	s_waitcnt vmcnt(63)
	v_add_f32_e32 v133, v44, v133
	global_store_dword v218, v133, s[8:9] offset:64
	s_waitcnt vmcnt(63)
	v_add_f32_e32 v134, v40, v134
	global_store_dword v218, v134, s[8:9] offset:128
	s_waitcnt vmcnt(63)
	v_add_f32_e32 v135, v36, v135
	global_store_dword v218, v135, s[8:9] offset:192
	s_waitcnt vmcnt(63)
	v_add_f32_e32 v136, v49, v136
	global_store_dword v219, v136, s[8:9]
	s_waitcnt vmcnt(63)
	v_add_f32_e32 v137, v45, v137
	global_store_dword v219, v137, s[8:9] offset:64
	s_waitcnt vmcnt(63)
	v_add_f32_e32 v138, v41, v138
	global_store_dword v219, v138, s[8:9] offset:128
	s_waitcnt vmcnt(63)
	v_add_f32_e32 v139, v37, v139
	global_store_dword v219, v139, s[8:9] offset:192
	s_waitcnt vmcnt(63)
	v_add_f32_e32 v140, v50, v140
	global_store_dword v220, v140, s[8:9]
	s_waitcnt vmcnt(63)
	v_add_f32_e32 v141, v46, v141
	global_store_dword v220, v141, s[8:9] offset:64
	s_waitcnt vmcnt(63)
	v_add_f32_e32 v142, v42, v142
	global_store_dword v220, v142, s[8:9] offset:128
	s_waitcnt vmcnt(63)
	v_add_f32_e32 v143, v38, v143
	global_store_dword v220, v143, s[8:9] offset:192
	s_waitcnt vmcnt(63)
	v_add_f32_e32 v144, v51, v144
	global_store_dword v221, v144, s[8:9]
	s_waitcnt vmcnt(63)
	v_add_f32_e32 v145, v47, v145
	global_store_dword v221, v145, s[8:9] offset:64
	s_waitcnt vmcnt(63)
	v_add_f32_e32 v146, v43, v146
	global_store_dword v221, v146, s[8:9] offset:128
	s_waitcnt vmcnt(63)
	v_add_f32_e32 v147, v39, v147
	global_store_dword v221, v147, s[8:9] offset:192
	s_waitcnt vmcnt(63)
	v_add_f32_e32 v148, v32, v148
	global_store_dword v222, v148, s[8:9]
	s_waitcnt vmcnt(63)
	v_add_f32_e32 v149, v28, v149
	global_store_dword v222, v149, s[8:9] offset:64
	s_waitcnt vmcnt(63)
	v_add_f32_e32 v150, v24, v150
	global_store_dword v222, v150, s[8:9] offset:128
	s_waitcnt vmcnt(63)
	v_add_f32_e32 v151, v20, v151
	global_store_dword v222, v151, s[8:9] offset:192
	s_waitcnt vmcnt(63)
	v_add_f32_e32 v152, v33, v152
	global_store_dword v223, v152, s[8:9]
	s_waitcnt vmcnt(63)
	v_add_f32_e32 v153, v29, v153
	global_store_dword v223, v153, s[8:9] offset:64
	s_waitcnt vmcnt(63)
	v_add_f32_e32 v154, v25, v154
	global_store_dword v223, v154, s[8:9] offset:128
	s_waitcnt vmcnt(63)
	v_add_f32_e32 v155, v21, v155
	global_store_dword v223, v155, s[8:9] offset:192
	s_waitcnt vmcnt(63)
	v_add_f32_e32 v156, v34, v156
	global_store_dword v224, v156, s[8:9]
	s_waitcnt vmcnt(63)
	v_add_f32_e32 v157, v30, v157
	global_store_dword v224, v157, s[8:9] offset:64
	s_waitcnt vmcnt(63)
	v_add_f32_e32 v158, v26, v158
	global_store_dword v224, v158, s[8:9] offset:128
	s_waitcnt vmcnt(63)
	v_add_f32_e32 v159, v22, v159
	global_store_dword v224, v159, s[8:9] offset:192
	s_waitcnt vmcnt(63)
	v_add_f32_e32 v160, v35, v160
	global_store_dword v225, v160, s[8:9]
	s_waitcnt vmcnt(63)
	v_add_f32_e32 v161, v31, v161
	global_store_dword v225, v161, s[8:9] offset:64
	s_waitcnt vmcnt(63)
	v_add_f32_e32 v162, v27, v162
	global_store_dword v225, v162, s[8:9] offset:128
	s_waitcnt vmcnt(63)
	v_add_f32_e32 v163, v23, v163
	global_store_dword v225, v163, s[8:9] offset:192
	s_waitcnt vmcnt(63)
	v_add_f32_e32 v164, v16, v164
	global_store_dword v226, v164, s[8:9]
	s_waitcnt vmcnt(63)
	v_add_f32_e32 v165, v12, v165
	global_store_dword v226, v165, s[8:9] offset:64
	s_waitcnt vmcnt(63)
	v_add_f32_e32 v166, v8, v166
	global_store_dword v226, v166, s[8:9] offset:128
	s_waitcnt vmcnt(63)
	v_add_f32_e32 v167, v4, v167
	global_store_dword v226, v167, s[8:9] offset:192
	s_waitcnt vmcnt(63)
	v_add_f32_e32 v168, v17, v168
	global_store_dword v227, v168, s[8:9]
	s_waitcnt vmcnt(63)
	v_add_f32_e32 v169, v13, v169
	global_store_dword v227, v169, s[8:9] offset:64
	s_waitcnt vmcnt(63)
	v_add_f32_e32 v170, v9, v170
	global_store_dword v227, v170, s[8:9] offset:128
	s_waitcnt vmcnt(63)
	v_add_f32_e32 v171, v5, v171
	global_store_dword v227, v171, s[8:9] offset:192
	s_waitcnt vmcnt(63)
	v_add_f32_e32 v172, v18, v172
	global_store_dword v228, v172, s[8:9]
	s_waitcnt vmcnt(63)
	v_add_f32_e32 v173, v14, v173
	global_store_dword v228, v173, s[8:9] offset:64
	s_waitcnt vmcnt(63)
	v_add_f32_e32 v174, v10, v174
	global_store_dword v228, v174, s[8:9] offset:128
	s_waitcnt vmcnt(63)
	v_add_f32_e32 v175, v6, v175
	global_store_dword v228, v175, s[8:9] offset:192
	s_waitcnt vmcnt(63)
	v_add_f32_e32 v176, v19, v176
	global_store_dword v229, v176, s[8:9]
	s_waitcnt vmcnt(63)
	v_add_f32_e32 v177, v15, v177
	global_store_dword v229, v177, s[8:9] offset:64
	s_waitcnt vmcnt(63)
	v_add_f32_e32 v178, v11, v178
	global_store_dword v229, v178, s[8:9] offset:128
	s_waitcnt vmcnt(63)
	v_add_f32_e32 v179, v7, v179
	global_store_dword v229, v179, s[8:9] offset:192
	s_add_i32 s27, s27, s96
	s_cmp_ge_i32 s27, s23
	s_cbranch_scc1 .LBB0_2028
